# GLA scan cache policy: non-temporal hint on the scan's single-use input streams (raw q/k dword loads, low-rank rows, V tile LDS-DMA) so they do not displace attention K/V tiles in L2
# baseline (speedup 1.0000x reference)
; __device__ __forceinline__ int v_st(int k, int c) { const int kk = (k & ~0xC) | ((k & 4) << 1) | ((k & 8) >> 1); return ((kk >> 3) * 4 + (c >> 5)) * 512 + ((kk & 7) * 32 + (c & 31)) * 2; }
; #define OPAQUE_TID(name) int name = MK_TID; asm volatile("" : "+v"(name))
; #define GLA_FLUSH() do { if (pend_cc >= 0) { OPAQUE_TID(tf_); const size_t rl0_ = (size_t)b * T + (size_t)(pend_cc - 4) * 64; \
;       _Pragma("unroll") for (int p = 0; p < 4; ++p) { const int idx_ = p * 512 + tf_, i_ = idx_ >> 5, c16_ = idx_ & 31; \
;           *(v4u*)(OUT + (rl0_ + (dir ? 63 - i_ : i_)) * 1024 + h * 256 + c16_ * 8) = *(const v4u*)(ot + i_ * 256 + c16_ * 8); } } } while (0)
; __device__ __forceinline__ void scan_unit(const int unit, const Args& a, unsigned char* lds, const int mk_wid) {
;     ...
;     f32x16 S[4]; S[0] = f32x16{}; S[1] = f32x16{}; S[2] = f32x16{}; S[3] = f32x16{};
;     bf16x8 qraw[2], kraw[2], vraw[4]; bf16x8 lraw = bf16x8{};
;     ...
;     GLA_LOAD(0);
;     for (int step = 0; step < 36; ++step) {
;         const int cc = GLA_CHUNK(step); const bool lat = cc >= 4;
;         GLA_FLUSH();
;         { OPAQUE_TID(t_);
; #pragma unroll
;           for (int p = 0; p < 2; ++p) { const int i_ = p * 32 + (t_ >> 4), c_ = (t_ & 15) * 8; *(bf16x8*)(qe + i_ * QP + c_) = qraw[p]; *(bf16x8*)(ke + i_ * QP + c_) = kraw[p]; }
; #pragma unroll
;           for (int p = 0; p < 4; ++p) { const int i_ = p * 16 + (t_ >> 5), c8 = t_ & 31; *(bf16x8*)(lds + L_V + (c8 >> 4) * 16384 + v_st(i_, (c8 & 15) * 8)) = vraw[p]; }
.Lscan_noflrd:
	v_add_u32_e32 v66, s96, v247
	v_add_u32_e32 v67, s96, v248
	v_add_u32_e32 v68, s96, v249
	v_add_u32_e32 v69, s96, v250
	s_mov_b32 m0, s97
	s_nop 0
	global_load_lds_dwordx4 v66, s[16:17] nt
	s_add_i32 m0, s97, 0x400
	s_nop 0
	global_load_lds_dwordx4 v67, s[16:17] nt
	s_add_i32 m0, s97, 0x800
	s_nop 0
	global_load_lds_dwordx4 v68, s[16:17] nt
	s_add_i32 m0, s97, 0xc00
	s_nop 0
	global_load_lds_dwordx4 v69, s[16:17] nt
	s_cmp_lt_i32 s34, 0
	s_cbranch_scc1 .Lscan_noflush
	s_ashr_i32 s35, s34, 31
	s_lshl_b64 s[26:27], s[34:35], 6
	s_add_u32 s26, s26, s20
	s_addc_u32 s27, s27, s21
	s_add_u32 s26, s26, 0xffffff00
	s_addc_u32 s27, s27, -1
	s_lshl_b64 s[26:27], s[26:27], 11
	s_add_u32 s26, s26, s18
	s_addc_u32 s27, s27, s19
	s_movk_i32 s98, 0x4000
	s_movk_i32 s99, 0xc000
	s_bitcmp1_b32 s8, 0
	s_cselect_b32 s98, s99, s98
	v_add_u32_e32 v165, s98, v252
	v_add_u32_e32 v166, s98, v165
	v_add_u32_e32 v167, s98, v166

.LBB0_426:
	s_lshl_b32 s26, s34, 16
	s_lshl_b32 s35, s34, 12
	v_add_u32_e32 v64, s26, v245
	v_add_u32_e32 v65, 0x1000, v64
	s_cmp_lt_i32 s34, 4
	s_cbranch_scc1 .Lscan_pf_noq
	s_bitcmp1_b32 s8, 0
	s_cbranch_scc1 .Lscan_qk_rev0
	global_load_dword v100, v64, s[14:15] nt
	global_load_dword v128, v64, s[22:23] nt
	global_load_dword v101, v64, s[14:15] offset:1024 nt
	global_load_dword v129, v64, s[22:23] offset:1024 nt
	global_load_dword v102, v64, s[14:15] offset:2048 nt
	global_load_dword v130, v64, s[22:23] offset:2048 nt
	global_load_dword v103, v64, s[14:15] offset:3072 nt
	global_load_dword v131, v64, s[22:23] offset:3072 nt
	global_load_dword v104, v65, s[14:15] nt
	global_load_dword v132, v65, s[22:23] nt
	global_load_dword v105, v65, s[14:15] offset:1024 nt
	global_load_dword v133, v65, s[22:23] offset:1024 nt
	global_load_dword v106, v65, s[14:15] offset:2048 nt
	global_load_dword v134, v65, s[22:23] offset:2048 nt
	global_load_dword v107, v65, s[14:15] offset:3072 nt
	global_load_dword v135, v65, s[22:23] offset:3072 nt
	s_branch .Lscan_qk_done0
.Lscan_qk_rev0:
	global_load_dword v100, v65, s[14:15] offset:3072 nt
	global_load_dword v128, v65, s[22:23] offset:3072 nt
	global_load_dword v101, v65, s[14:15] offset:2048 nt
	global_load_dword v129, v65, s[22:23] offset:2048 nt
	global_load_dword v102, v65, s[14:15] offset:1024 nt
	global_load_dword v130, v65, s[22:23] offset:1024 nt
	global_load_dword v103, v65, s[14:15] nt
	global_load_dword v131, v65, s[22:23] nt
	global_load_dword v104, v64, s[14:15] offset:3072 nt
	global_load_dword v132, v64, s[22:23] offset:3072 nt
	global_load_dword v105, v64, s[14:15] offset:2048 nt
	global_load_dword v133, v64, s[22:23] offset:2048 nt
	global_load_dword v106, v64, s[14:15] offset:1024 nt
	global_load_dword v134, v64, s[22:23] offset:1024 nt
	global_load_dword v107, v64, s[14:15] nt
	global_load_dword v135, v64, s[22:23] nt

.Lscan_pf_noq:
	s_bitcmp1_b32 s8, 0
	s_cbranch_scc1 .Lscan_qk_rev1
	global_load_dword v100, v64, s[14:15] nt
	global_load_dword v101, v64, s[14:15] offset:1024 nt
	global_load_dword v102, v64, s[14:15] offset:2048 nt
	global_load_dword v103, v64, s[14:15] offset:3072 nt
	global_load_dword v104, v65, s[14:15] nt
	global_load_dword v105, v65, s[14:15] offset:1024 nt
	global_load_dword v106, v65, s[14:15] offset:2048 nt
	global_load_dword v107, v65, s[14:15] offset:3072 nt
	s_branch .Lscan_qk_done1
.Lscan_qk_rev1:
	global_load_dword v100, v65, s[14:15] offset:3072 nt
	global_load_dword v101, v65, s[14:15] offset:2048 nt
	global_load_dword v102, v65, s[14:15] offset:1024 nt
	global_load_dword v103, v65, s[14:15] nt
	global_load_dword v104, v64, s[14:15] offset:3072 nt
	global_load_dword v105, v64, s[14:15] offset:2048 nt
	global_load_dword v106, v64, s[14:15] offset:1024 nt
	global_load_dword v107, v64, s[14:15] nt

.Lscan_pf_v:
	v_add_u32_e32 v70, s35, v251
	v_mov_b32_e32 v71, 0
	v_lshl_add_u64 v[70:71], v[152:153], 0, v[70:71]
	global_load_dwordx4 v[96:99], v[70:71], off nt
